# GEMM: last k-tile's spare LDS-DMA slot fetches the CU's next tile (k-tile 0) so chained tiles skip prologue DMA+waits+barriers
# speedup vs baseline: 1.1285x; 1.0111x over previous
; DI unsigned voff256(size_t ld) { const int t = tid512(); return (unsigned)(((size_t)(t >> 3) * ld + (t & 7) * 8) * 2); }
; DI int tile_of(int i, int ntiles) {
;   const int G = gridDim.x, b = blockIdx.x;
;   if (G & 7) { int L = b + i * G; return L < ntiles ? L : -1; }
;   const int q = (ntiles + 7) >> 3, nb = G >> 3, x = b & 7, loc = (b >> 3) + i * nb;
;   if (loc >= q) return -1;
;   const int L = x * q + loc;
;   return L < ntiles ? L : -1;
; }
; DI void inproj_phase(const Params& p, int layer, char* smem) {
;   const bf16_t* H = (const bf16_t*)(p.ws + O_H);
;   const bf16_t* W = (const bf16_t*)(p.ws + O_WIN) + (size_t)layer * DIN * DM;
;   for (int i = 0;; ++i) {
;     const int L = tile_of(i, 32 * 24);
;     if (L < 0) break;
;     int tm, tn; tile_mn(L, 32, 24, tm, tn);
;     f32x16 acc[4][2]; zero_acc256(acc);
;     gemm256((const char*)(W + (size_t)(tn * 256) * DM), voff256(DM), (size_t)128 * DM, (const char*)(H + (size_t)(256 + tm * 256) * DM), voff256(DM), (size_t)128 * DM, DM / 64, smem, acc);
.LBB0_188:
	s_mul_hi_u32 s6, s8, 0xaaaaaaab
	s_lshr_b32 s6, s6, 6
	s_lshl_b32 s9, s6, 2
	s_sub_i32 s7, 32, s9
	s_min_i32 s10, s7, 4
	s_abs_i32 s7, s10
	v_cvt_f32_u32_e32 v2, s7
	s_sub_i32 s12, 0, s7
	s_mulk_i32 s6, 0xffa0
	s_add_i32 s6, s6, s8
	v_rcp_iflag_f32_e32 v2, v2
	s_abs_i32 s8, s6
	s_xor_b32 s11, s6, s10
	s_ashr_i32 s11, s11, 31
	v_mul_f32_e32 v2, 0x4f7ffffe, v2
	v_cvt_u32_f32_e32 v2, v2
	s_movk_i32 s16, 0xf000
	v_mov_b32_e32 v37, v181
	v_readfirstlane_b32 s13, v2
	s_mul_i32 s12, s12, s13
	s_mul_hi_u32 s12, s13, s12
	s_add_i32 s13, s13, s12
	s_mul_hi_u32 s12, s8, s13
	s_mul_i32 s13, s12, s7
	s_sub_i32 s8, s8, s13
	s_add_i32 s14, s12, 1
	s_sub_i32 s13, s8, s7
	s_cmp_ge_u32 s8, s7
	s_cselect_b32 s12, s14, s12
	s_cselect_b32 s8, s13, s8
	s_add_i32 s13, s12, 1
	s_cmp_ge_u32 s8, s7
	s_cselect_b32 s7, s13, s12
	s_xor_b32 s7, s7, s11
	s_sub_i32 s7, s7, s11
	s_mul_i32 s10, s7, s10
	s_lshl_b32 s8, s7, 8
	s_sub_i32 s6, s6, s10
	s_add_i32 s6, s6, s9
	s_ashr_i32 s9, s8, 31
	s_lshl_b64 s[8:9], s[8:9], 12
	s_add_u32 s12, s0, s8
	v_mov_b32_e32 v2, v0
	s_addc_u32 s13, s1, s9
	s_lshl_b32 s6, s6, 8
	v_lshlrev_b32_e32 v3, 4, v2
	v_and_b32_e32 v3, 0x70, v3
	v_lshlrev_b32_e32 v2, 9, v2
	s_add_i32 s8, s6, 0x100
	v_and_or_b32 v180, v2, s16, v3
	s_ashr_i32 s9, s8, 31
	v_mov_b32_e32 v2, v0
	s_lshl_b64 s[10:11], s[8:9], 12
	s_add_u32 s14, s92, s10
	v_lshlrev_b32_e32 v3, 4, v2
	v_and_b32_e32 v3, 0x70, v3
	v_lshlrev_b32_e32 v2, 9, v2
	v_lshl_add_u64 v[162:163], s[12:13], 0, v[180:181]
	s_addc_u32 s15, s93, s11
	v_and_or_b32 v36, v2, s16, v3
	v_add_co_u32_e32 v12, vcc, s84, v162
	v_lshl_add_u64 v[164:165], s[14:15], 0, v[36:37]
	s_nop 0
	v_addc_co_u32_e32 v13, vcc, 0, v163, vcc
	v_add_co_u32_e32 v16, vcc, s84, v164
	s_mov_b32 s9, 32
	s_nop 0
	v_addc_co_u32_e32 v17, vcc, 0, v165, vcc
	v_add_co_u32_e32 v20, vcc, s31, v162
	s_add_i32 s10, s9, -1
	s_nop 0
	v_addc_co_u32_e32 v21, vcc, 0, v163, vcc
	s_min_i32 s11, s10, 1
	v_add_co_u32_e32 v24, vcc, s31, v164
	s_lshl_b32 s11, s11, 7
	v_mov_b32_e32 v2, v0
	v_addc_co_u32_e32 v25, vcc, 0, v165, vcc
	s_ashr_i32 s16, s11, 31
	v_lshrrev_b32_e32 v132, 6, v0
	s_nop 0
	v_readfirstlane_b32 s61, v132
	v_and_b32_e32 v132, 63, v0
	v_and_b32_e32 v133, 31, v132
	v_lshrrev_b32_e32 v136, 5, v132
	v_bfe_u32 v137, v133, 1, 3
	v_lshlrev_b32_e32 v133, 7, v133
	s_lshr_b32 s60, s61, 2
	s_lshl_b32 s60, s60, 14
	s_add_i32 s60, s60, 16
	s_and_b32 s62, s61, 3
	s_lshl_b32 s62, s62, 13
	s_add_i32 s62, s62, 0x10010
	v_add_u32_e32 v194, 0, v136
	v_xor_b32_e32 v194, v194, v137
	v_lshl_add_u32 v194, v194, 4, v133
	v_add_u32_e32 v160, s62, v194
	v_add_u32_e32 v194, s60, v194
	v_add_u32_e32 v195, 2, v136
	v_xor_b32_e32 v195, v195, v137
	v_lshl_add_u32 v195, v195, 4, v133
	v_add_u32_e32 v161, s62, v195
	v_add_u32_e32 v195, s60, v195
	v_add_u32_e32 v250, 4, v136
	v_xor_b32_e32 v250, v250, v137
	v_lshl_add_u32 v250, v250, 4, v133
	v_add_u32_e32 v162, s62, v250
	v_add_u32_e32 v250, s60, v250
	v_add_u32_e32 v251, 6, v136
	v_xor_b32_e32 v251, v251, v137
	v_lshl_add_u32 v251, v251, 4, v133
	v_add_u32_e32 v163, s62, v251
	v_add_u32_e32 v251, s60, v251
	v_lshrrev_b32_e32 v133, 3, v132
	s_mov_b32 s60, 0x1000
	v_mul_lo_u32 v133, v133, s60
	v_and_b32_e32 v136, 7, v132
	v_lshrrev_b32_e32 v137, 4, v132
	v_xor_b32_e32 v164, v137, v136
	v_lshl_add_u32 v164, v164, 4, v133
	v_add_u32_e32 v165, 4, v137
	v_xor_b32_e32 v165, v165, v136
	v_lshl_add_u32 v165, v165, 4, v133
	v_add_u32_e32 v165, 0x8000, v165
	v_xor_b32_e32 v130, v137, v136
	v_lshl_add_u32 v130, v130, 4, v133
	v_add_u32_e32 v130, 0x10000, v130
	v_add_u32_e32 v131, 4, v137
	v_xor_b32_e32 v131, v131, v136
	v_lshl_add_u32 v131, v131, 4, v133
	v_add_u32_e32 v131, 0x18000, v131
	s_mul_i32 s60, s61, 0x20000
	s_add_u32 s52, s12, s60
	s_addc_u32 s53, s13, 0
	s_add_u32 s54, s14, s60
	s_addc_u32 s55, s15, 0
	s_lshl_b32 s58, s61, 12
	s_add_i32 s58, s58, 16
	s_add_i32 s59, s58, 0x10000
	s_mov_b32 s56, 0
	s_mov_b32 s57, 31
	s_add_u32 s64, s52, 0x800000
	s_addc_u32 s65, s53, 0
	s_add_u32 s66, s54, 0x0
	s_addc_u32 s67, s55, 0
	s_and_b64 s[62:63], exec, s[40:41]
	s_cselect_b32 s62, 0, 1
	s_add_i32 s60, s22, 1
	s_mul_i32 s60, s60, s88
	s_add_i32 s60, s60, s33
	s_cmp_lt_u32 s60, 96
	s_cselect_b32 s63, s57, -1
	s_cmp_eq_u32 s62, 1
	s_cselect_b32 s63, -1, s63
	s_cbranch_scc1 .Lg_inproj_first
	s_cmp_eq_u32 s22, 0
	s_cbranch_scc1 .Lg_inproj_first
	s_cmp_lt_u32 s56, s57
	s_cselect_b32 s60, 0x80, 0
	s_add_u32 s52, s52, s60
	s_addc_u32 s53, s53, 0
	s_add_u32 s54, s54, s60
	s_addc_u32 s55, s55, 0
	s_cmp_eq_u32 s56, s63
	s_cselect_b32 s52, s64, s52
	s_cselect_b32 s53, s65, s53
	s_cselect_b32 s54, s66, s54
	s_cselect_b32 s55, s67, s55
	v_mov_b64_e32 v[114:115], 0
	v_mov_b64_e32 v[116:117], 0
	v_mov_b64_e32 v[118:119], 0
	v_mov_b64_e32 v[120:121], 0
	v_mov_b64_e32 v[122:123], 0
	v_mov_b64_e32 v[124:125], 0
	v_mov_b64_e32 v[126:127], 0
	v_mov_b64_e32 v[128:129], 0
	v_mov_b64_e32 v[50:51], 0
	v_mov_b64_e32 v[52:53], 0
	v_mov_b64_e32 v[54:55], 0
	v_mov_b64_e32 v[56:57], 0
	v_mov_b64_e32 v[58:59], 0
	v_mov_b64_e32 v[60:61], 0
	v_mov_b64_e32 v[62:63], 0
	v_mov_b64_e32 v[64:65], 0
	v_mov_b64_e32 v[98:99], 0
	v_mov_b64_e32 v[100:101], 0
	v_mov_b64_e32 v[102:103], 0
	v_mov_b64_e32 v[104:105], 0
	v_mov_b64_e32 v[106:107], 0
	v_mov_b64_e32 v[108:109], 0
	v_mov_b64_e32 v[110:111], 0
	v_mov_b64_e32 v[112:113], 0
	v_mov_b64_e32 v[34:35], 0
	v_mov_b64_e32 v[36:37], 0
	v_mov_b64_e32 v[38:39], 0
	v_mov_b64_e32 v[40:41], 0
	v_mov_b64_e32 v[42:43], 0
	v_mov_b64_e32 v[44:45], 0
	v_mov_b64_e32 v[46:47], 0
	v_mov_b64_e32 v[48:49], 0
	v_mov_b64_e32 v[82:83], 0
	v_mov_b64_e32 v[84:85], 0
	v_mov_b64_e32 v[86:87], 0
	v_mov_b64_e32 v[88:89], 0
	v_mov_b64_e32 v[90:91], 0
	v_mov_b64_e32 v[92:93], 0
	v_mov_b64_e32 v[94:95], 0
	v_mov_b64_e32 v[96:97], 0
	v_mov_b64_e32 v[18:19], 0
	v_mov_b64_e32 v[20:21], 0
	v_mov_b64_e32 v[22:23], 0
	v_mov_b64_e32 v[24:25], 0
	v_mov_b64_e32 v[26:27], 0
	v_mov_b64_e32 v[28:29], 0
	v_mov_b64_e32 v[30:31], 0
	v_mov_b64_e32 v[32:33], 0
	v_mov_b64_e32 v[66:67], 0
	v_mov_b64_e32 v[68:69], 0
	v_mov_b64_e32 v[70:71], 0
	v_mov_b64_e32 v[72:73], 0
	v_mov_b64_e32 v[74:75], 0
	v_mov_b64_e32 v[76:77], 0
	v_mov_b64_e32 v[78:79], 0
	v_mov_b64_e32 v[80:81], 0
	v_mov_b64_e32 v[2:3], 0
	v_mov_b64_e32 v[4:5], 0
	v_mov_b64_e32 v[6:7], 0
	v_mov_b64_e32 v[8:9], 0
	v_mov_b64_e32 v[10:11], 0
	v_mov_b64_e32 v[12:13], 0
	v_mov_b64_e32 v[14:15], 0
	v_mov_b64_e32 v[16:17], 0
	s_branch .Lg_inproj_go
; #define MFMA32(a, b, c) __builtin_amdgcn_mfma_f32_32x32x16_bf16((a), (b), (c), 0, 0, 0)
; DI int tid512() { int t = threadIdx.x; asm volatile("" : "+v"(t)); return t; }
; DI void gemm256(const char* a_u, unsigned a_voff, size_t astep, const char* b_u, unsigned b_voff, size_t bstep, int nk, char* smem, f32x16 (&acc)[4][2]) {
;   asm volatile("" : "+s"(nk));
;   const int t = tid512(), lane = t & 63, w = t >> 6, wm = w >> 2, wn = w & 3, r = lane & 31, h = lane >> 5;
;   const int soff = (t >> 3) * LROW + (t & 7) * 16;
;   const int aoff = (128 * wm + r) * LROW + h * 16, boff = T2 + (64 * wn + r) * LROW + h * 16;
;   u32x4 ra[4], rb[4];
; #pragma unroll
;   for (int i = 0; i < 4; ++i) { ra[i] = *(const u32x4*)(a_u + i * astep + a_voff); rb[i] = *(const u32x4*)(b_u + i * bstep + b_voff); }
;   __syncthreads();
; #pragma unroll
;   for (int i = 0; i < 4; ++i) { *(u32x4*)(smem + soff + i * 64 * LROW) = ra[i]; *(u32x4*)(smem + T2 + soff + i * 64 * LROW) = rb[i]; }
;   const int last = nk - 1;
;   {
;     const int k1 = last < 1 ? last : 1;
; #pragma unroll
;     for (int i = 0; i < 4; ++i) { ra[i] = *(const u32x4*)(a_u + i * astep + k1 * 128 + a_voff); rb[i] = *(const u32x4*)(b_u + i * bstep + k1 * 128 + b_voff); }
;   }
;   __syncthreads();
;   for (int kt = 0; kt < nk; ++kt) {
;     const int cur = kt & 1, k2 = (kt + 2 < last) ? kt + 2 : last;
;     const char* S = smem + cur * 2 * T2;
;     char* D = smem + (cur ^ 1) * 2 * T2;
;     const char* an = a_u + (size_t)k2 * 128;
;     const char* bn = b_u + (size_t)k2 * 128;
; #pragma unroll
;     for (int s = 0; s < 4; ++s) {
;       bf16x8 a[4], b[2];
; #pragma unroll
;       for (int mi = 0; mi < 4; ++mi) a[mi] = *(const bf16x8*)(S + aoff + mi * 32 * LROW + s * 32);
; #pragma unroll
;       for (int ni = 0; ni < 2; ++ni) b[ni] = *(const bf16x8*)(S + boff + ni * 32 * LROW + s * 32);
;       *(u32x4*)(D + soff + s * 64 * LROW) = ra[s];
;       *(u32x4*)(D + T2 + soff + s * 64 * LROW) = rb[s];
;       ra[s] = *(const u32x4*)(an + s * astep + a_voff);
;       rb[s] = *(const u32x4*)(bn + s * bstep + b_voff);
; #pragma unroll
;       for (int mi = 0; mi < 4; ++mi)
; #pragma unroll
;         for (int ni = 0; ni < 2; ++ni) acc[mi][ni] = MFMA32(a[mi], b[ni], acc[mi][ni]);
;     }
;     __syncthreads();
;   }
.Lg_inproj_first:
	s_barrier
	s_add_u32 m0, s58, 0x0
	s_nop 0
	global_load_lds_dwordx4 v164, s[52:53]
	s_add_u32 m0, s58, 0x400
	s_nop 0
	global_load_lds_dwordx4 v165, s[52:53]
	s_add_u32 m0, s58, 0x800
	s_nop 0
	global_load_lds_dwordx4 v130, s[52:53]
	s_add_u32 m0, s58, 0xc00
	s_nop 0
	global_load_lds_dwordx4 v131, s[52:53]
	s_add_u32 m0, s59, 0x0
	s_nop 0
	global_load_lds_dwordx4 v164, s[54:55]
	s_add_u32 m0, s59, 0x400
	s_nop 0
	global_load_lds_dwordx4 v165, s[54:55]
	s_add_u32 m0, s59, 0x800
	s_nop 0
	global_load_lds_dwordx4 v130, s[54:55]
	s_add_u32 m0, s59, 0xc00
	s_nop 0
	global_load_lds_dwordx4 v131, s[54:55]
	s_cmp_lt_u32 s56, s57
	s_cselect_b32 s60, 0x80, 0
	s_add_u32 s52, s52, s60
	s_addc_u32 s53, s53, 0
	s_add_u32 s54, s54, s60
	s_addc_u32 s55, s55, 0
	s_cmp_eq_u32 s56, s63
	s_cselect_b32 s52, s64, s52
	s_cselect_b32 s53, s65, s53
	s_cselect_b32 s54, s66, s54
	s_cselect_b32 s55, s67, s55
	v_mov_b64_e32 v[114:115], 0
	v_mov_b64_e32 v[116:117], 0
	v_mov_b64_e32 v[118:119], 0
	v_mov_b64_e32 v[120:121], 0
	v_mov_b64_e32 v[122:123], 0
	v_mov_b64_e32 v[124:125], 0
	v_mov_b64_e32 v[126:127], 0
	v_mov_b64_e32 v[128:129], 0
	v_mov_b64_e32 v[50:51], 0
	v_mov_b64_e32 v[52:53], 0
	v_mov_b64_e32 v[54:55], 0
	v_mov_b64_e32 v[56:57], 0
	v_mov_b64_e32 v[58:59], 0
	v_mov_b64_e32 v[60:61], 0
	v_mov_b64_e32 v[62:63], 0
	v_mov_b64_e32 v[64:65], 0
	v_mov_b64_e32 v[98:99], 0
	v_mov_b64_e32 v[100:101], 0
	v_mov_b64_e32 v[102:103], 0
	v_mov_b64_e32 v[104:105], 0
	v_mov_b64_e32 v[106:107], 0
	v_mov_b64_e32 v[108:109], 0
	v_mov_b64_e32 v[110:111], 0
	v_mov_b64_e32 v[112:113], 0
	v_mov_b64_e32 v[34:35], 0
	v_mov_b64_e32 v[36:37], 0
	v_mov_b64_e32 v[38:39], 0
	v_mov_b64_e32 v[40:41], 0
	v_mov_b64_e32 v[42:43], 0
	v_mov_b64_e32 v[44:45], 0
	v_mov_b64_e32 v[46:47], 0
	v_mov_b64_e32 v[48:49], 0
	v_mov_b64_e32 v[82:83], 0
	v_mov_b64_e32 v[84:85], 0
	v_mov_b64_e32 v[86:87], 0
	v_mov_b64_e32 v[88:89], 0
	v_mov_b64_e32 v[90:91], 0
	v_mov_b64_e32 v[92:93], 0
	v_mov_b64_e32 v[94:95], 0
	v_mov_b64_e32 v[96:97], 0
	v_mov_b64_e32 v[18:19], 0
	v_mov_b64_e32 v[20:21], 0
	v_mov_b64_e32 v[22:23], 0
	v_mov_b64_e32 v[24:25], 0
	v_mov_b64_e32 v[26:27], 0
	v_mov_b64_e32 v[28:29], 0
	v_mov_b64_e32 v[30:31], 0
	v_mov_b64_e32 v[32:33], 0
	v_mov_b64_e32 v[66:67], 0
	v_mov_b64_e32 v[68:69], 0
	v_mov_b64_e32 v[70:71], 0
	v_mov_b64_e32 v[72:73], 0
	v_mov_b64_e32 v[74:75], 0
	v_mov_b64_e32 v[76:77], 0
	v_mov_b64_e32 v[78:79], 0
	v_mov_b64_e32 v[80:81], 0
	v_mov_b64_e32 v[2:3], 0
	v_mov_b64_e32 v[4:5], 0
	v_mov_b64_e32 v[6:7], 0
	v_mov_b64_e32 v[8:9], 0
	v_mov_b64_e32 v[10:11], 0
	v_mov_b64_e32 v[12:13], 0
	v_mov_b64_e32 v[14:15], 0
	v_mov_b64_e32 v[16:17], 0
	s_waitcnt vmcnt(0)
	s_barrier
.Lg_inproj_go:
	ds_read_b128 v[196:199], v194 offset:0
	ds_read_b128 v[212:215], v160 offset:0
	ds_read_b128 v[216:219], v160 offset:4096
	ds_read_b128 v[200:203], v194 offset:4096
	ds_read_b128 v[204:207], v194 offset:8192
	ds_read_b128 v[208:211], v194 offset:12288
.Lg_inproj_loop:
	s_add_i32 s56, s56, 1
	s_add_u32 m0, s58, 0x8000
	s_nop 0
	global_load_lds_dwordx4 v164, s[52:53]
	s_add_u32 m0, s58, 0x8400
	s_nop 0
	global_load_lds_dwordx4 v165, s[52:53]
	s_add_u32 m0, s58, 0x8800
	s_nop 0
	global_load_lds_dwordx4 v130, s[52:53]
	s_add_u32 m0, s58, 0x8c00
	s_nop 0
	global_load_lds_dwordx4 v131, s[52:53]
	s_add_u32 m0, s59, 0x8000
	s_nop 0
	global_load_lds_dwordx4 v164, s[54:55]
	s_add_u32 m0, s59, 0x8400
	s_nop 0
	global_load_lds_dwordx4 v165, s[54:55]
	s_add_u32 m0, s59, 0x8800
	s_nop 0
	global_load_lds_dwordx4 v130, s[54:55]
	s_add_u32 m0, s59, 0x8c00
	s_nop 0
	global_load_lds_dwordx4 v131, s[54:55]
	s_waitcnt lgkmcnt(0)
	v_mfma_f32_32x32x16_bf16 v[114:129], v[196:199], v[212:215], v[114:129]
	ds_read_b128 v[220:223], v195 offset:0
	ds_read_b128 v[242:245], v161 offset:0
	v_mfma_f32_32x32x16_bf16 v[50:65], v[196:199], v[216:219], v[50:65]
	ds_read_b128 v[246:249], v161 offset:4096
	ds_read_b128 v[224:227], v195 offset:4096
	v_mfma_f32_32x32x16_bf16 v[98:113], v[200:203], v[212:215], v[98:113]
	ds_read_b128 v[228:231], v195 offset:8192
	ds_read_b128 v[238:241], v195 offset:12288
	v_mfma_f32_32x32x16_bf16 v[34:49], v[200:203], v[216:219], v[34:49]
	v_mfma_f32_32x32x16_bf16 v[82:97], v[204:207], v[212:215], v[82:97]
	v_mfma_f32_32x32x16_bf16 v[18:33], v[204:207], v[216:219], v[18:33]
	v_mfma_f32_32x32x16_bf16 v[66:81], v[208:211], v[212:215], v[66:81]
	v_mfma_f32_32x32x16_bf16 v[2:17], v[208:211], v[216:219], v[2:17]
	s_waitcnt lgkmcnt(0)
	v_mfma_f32_32x32x16_bf16 v[114:129], v[220:223], v[242:245], v[114:129]
	ds_read_b128 v[196:199], v250 offset:0
	ds_read_b128 v[212:215], v162 offset:0
	v_mfma_f32_32x32x16_bf16 v[50:65], v[220:223], v[246:249], v[50:65]
	ds_read_b128 v[216:219], v162 offset:4096
	ds_read_b128 v[200:203], v250 offset:4096
	v_mfma_f32_32x32x16_bf16 v[98:113], v[224:227], v[242:245], v[98:113]
	ds_read_b128 v[204:207], v250 offset:8192
	ds_read_b128 v[208:211], v250 offset:12288
	v_mfma_f32_32x32x16_bf16 v[34:49], v[224:227], v[246:249], v[34:49]
	v_mfma_f32_32x32x16_bf16 v[82:97], v[228:231], v[242:245], v[82:97]
	v_mfma_f32_32x32x16_bf16 v[18:33], v[228:231], v[246:249], v[18:33]
	v_mfma_f32_32x32x16_bf16 v[66:81], v[238:241], v[242:245], v[66:81]
	v_mfma_f32_32x32x16_bf16 v[2:17], v[238:241], v[246:249], v[2:17]
	s_waitcnt lgkmcnt(0)
	v_mfma_f32_32x32x16_bf16 v[114:129], v[196:199], v[212:215], v[114:129]
	ds_read_b128 v[220:223], v251 offset:0
	ds_read_b128 v[242:245], v163 offset:0
	v_mfma_f32_32x32x16_bf16 v[50:65], v[196:199], v[216:219], v[50:65]
	ds_read_b128 v[246:249], v163 offset:4096
	ds_read_b128 v[224:227], v251 offset:4096
	v_mfma_f32_32x32x16_bf16 v[98:113], v[200:203], v[212:215], v[98:113]
	ds_read_b128 v[228:231], v251 offset:8192
	ds_read_b128 v[238:241], v251 offset:12288
	v_mfma_f32_32x32x16_bf16 v[34:49], v[200:203], v[216:219], v[34:49]
	s_cmp_lt_u32 s56, s57
	s_cselect_b32 s60, 0x80, 0
	s_add_u32 s52, s52, s60
	s_addc_u32 s53, s53, 0
	s_add_u32 s54, s54, s60
	s_addc_u32 s55, s55, 0
	s_cmp_eq_u32 s56, s63
	s_cselect_b32 s52, s64, s52
	s_cselect_b32 s53, s65, s53
	s_cselect_b32 s54, s66, s54
	s_cselect_b32 s55, s67, s55
	v_mfma_f32_32x32x16_bf16 v[82:97], v[204:207], v[212:215], v[82:97]
	v_mfma_f32_32x32x16_bf16 v[18:33], v[204:207], v[216:219], v[18:33]
	v_mfma_f32_32x32x16_bf16 v[66:81], v[208:211], v[212:215], v[66:81]
	v_mfma_f32_32x32x16_bf16 v[2:17], v[208:211], v[216:219], v[2:17]
	s_waitcnt lgkmcnt(0)
	v_mfma_f32_32x32x16_bf16 v[114:129], v[220:223], v[242:245], v[114:129]
	v_mfma_f32_32x32x16_bf16 v[50:65], v[220:223], v[246:249], v[50:65]
	v_mfma_f32_32x32x16_bf16 v[98:113], v[224:227], v[242:245], v[98:113]
	v_mfma_f32_32x32x16_bf16 v[34:49], v[224:227], v[246:249], v[34:49]
	v_mfma_f32_32x32x16_bf16 v[82:97], v[228:231], v[242:245], v[82:97]
	v_mfma_f32_32x32x16_bf16 v[18:33], v[228:231], v[246:249], v[18:33]
	v_mfma_f32_32x32x16_bf16 v[66:81], v[238:241], v[242:245], v[66:81]
	v_mfma_f32_32x32x16_bf16 v[2:17], v[238:241], v[246:249], v[2:17]
	s_waitcnt vmcnt(0)
	s_barrier
; #define MFMA32(a, b, c) __builtin_amdgcn_mfma_f32_32x32x16_bf16((a), (b), (c), 0, 0, 0)
; DI void gemm256(const char* a_u, unsigned a_voff, size_t astep, const char* b_u, unsigned b_voff, size_t bstep, int nk, char* smem, f32x16 (&acc)[4][2]) {
;     ...
;   for (int kt = 0; kt < nk; ++kt) {
;     const int cur = kt & 1, k2 = (kt + 2 < last) ? kt + 2 : last;
;     const char* S = smem + cur * 2 * T2;
;     char* D = smem + (cur ^ 1) * 2 * T2;
;     const char* an = a_u + (size_t)k2 * 128;
;     const char* bn = b_u + (size_t)k2 * 128;
; #pragma unroll
;     for (int s = 0; s < 4; ++s) {
;       bf16x8 a[4], b[2];
; #pragma unroll
;       for (int mi = 0; mi < 4; ++mi) a[mi] = *(const bf16x8*)(S + aoff + mi * 32 * LROW + s * 32);
; #pragma unroll
;       for (int ni = 0; ni < 2; ++ni) b[ni] = *(const bf16x8*)(S + boff + ni * 32 * LROW + s * 32);
;       *(u32x4*)(D + soff + s * 64 * LROW) = ra[s];
;       *(u32x4*)(D + T2 + soff + s * 64 * LROW) = rb[s];
;       ra[s] = *(const u32x4*)(an + s * astep + a_voff);
;       rb[s] = *(const u32x4*)(bn + s * bstep + b_voff);
; #pragma unroll
;       for (int mi = 0; mi < 4; ++mi)
; #pragma unroll
;         for (int ni = 0; ni < 2; ++ni) acc[mi][ni] = MFMA32(a[mi], b[ni], acc[mi][ni]);
;     }
;     __syncthreads();
;   }
	ds_read_b128 v[196:199], v194 offset:32768
	ds_read_b128 v[212:215], v160 offset:32768
	ds_read_b128 v[216:219], v160 offset:36864
	ds_read_b128 v[200:203], v194 offset:36864
	ds_read_b128 v[204:207], v194 offset:40960
	ds_read_b128 v[208:211], v194 offset:45056
	s_add_i32 s56, s56, 1
	s_add_u32 m0, s58, 0x0
	s_nop 0
	global_load_lds_dwordx4 v164, s[52:53]
	s_add_u32 m0, s58, 0x400
	s_nop 0
	global_load_lds_dwordx4 v165, s[52:53]
	s_add_u32 m0, s58, 0x800
	s_nop 0
	global_load_lds_dwordx4 v130, s[52:53]
	s_add_u32 m0, s58, 0xc00
	s_nop 0
	global_load_lds_dwordx4 v131, s[52:53]
	s_add_u32 m0, s59, 0x0
	s_nop 0
	global_load_lds_dwordx4 v164, s[54:55]
	s_add_u32 m0, s59, 0x400
	s_nop 0
	global_load_lds_dwordx4 v165, s[54:55]
	s_add_u32 m0, s59, 0x800
	s_nop 0
	global_load_lds_dwordx4 v130, s[54:55]
	s_add_u32 m0, s59, 0xc00
	s_nop 0
	global_load_lds_dwordx4 v131, s[54:55]
	s_waitcnt lgkmcnt(0)
	v_mfma_f32_32x32x16_bf16 v[114:129], v[196:199], v[212:215], v[114:129]
	ds_read_b128 v[220:223], v195 offset:32768
	ds_read_b128 v[242:245], v161 offset:32768
	v_mfma_f32_32x32x16_bf16 v[50:65], v[196:199], v[216:219], v[50:65]
	ds_read_b128 v[246:249], v161 offset:36864
	ds_read_b128 v[224:227], v195 offset:36864
	v_mfma_f32_32x32x16_bf16 v[98:113], v[200:203], v[212:215], v[98:113]
	ds_read_b128 v[228:231], v195 offset:40960
	ds_read_b128 v[238:241], v195 offset:45056
	v_mfma_f32_32x32x16_bf16 v[34:49], v[200:203], v[216:219], v[34:49]
	v_mfma_f32_32x32x16_bf16 v[82:97], v[204:207], v[212:215], v[82:97]
	v_mfma_f32_32x32x16_bf16 v[18:33], v[204:207], v[216:219], v[18:33]
	v_mfma_f32_32x32x16_bf16 v[66:81], v[208:211], v[212:215], v[66:81]
	v_mfma_f32_32x32x16_bf16 v[2:17], v[208:211], v[216:219], v[2:17]
	s_waitcnt lgkmcnt(0)
	v_mfma_f32_32x32x16_bf16 v[114:129], v[220:223], v[242:245], v[114:129]
	ds_read_b128 v[196:199], v250 offset:32768
	ds_read_b128 v[212:215], v162 offset:32768
	v_mfma_f32_32x32x16_bf16 v[50:65], v[220:223], v[246:249], v[50:65]
	ds_read_b128 v[216:219], v162 offset:36864
	ds_read_b128 v[200:203], v250 offset:36864
	v_mfma_f32_32x32x16_bf16 v[98:113], v[224:227], v[242:245], v[98:113]
	ds_read_b128 v[204:207], v250 offset:40960
	ds_read_b128 v[208:211], v250 offset:45056
	v_mfma_f32_32x32x16_bf16 v[34:49], v[224:227], v[246:249], v[34:49]
	v_mfma_f32_32x32x16_bf16 v[82:97], v[228:231], v[242:245], v[82:97]
	v_mfma_f32_32x32x16_bf16 v[18:33], v[228:231], v[246:249], v[18:33]
	v_mfma_f32_32x32x16_bf16 v[66:81], v[238:241], v[242:245], v[66:81]
	v_mfma_f32_32x32x16_bf16 v[2:17], v[238:241], v[246:249], v[2:17]
	s_waitcnt lgkmcnt(0)
	v_mfma_f32_32x32x16_bf16 v[114:129], v[196:199], v[212:215], v[114:129]
	ds_read_b128 v[220:223], v251 offset:32768
	ds_read_b128 v[242:245], v163 offset:32768
	v_mfma_f32_32x32x16_bf16 v[50:65], v[196:199], v[216:219], v[50:65]
	ds_read_b128 v[246:249], v163 offset:36864
	ds_read_b128 v[224:227], v251 offset:36864
	v_mfma_f32_32x32x16_bf16 v[98:113], v[200:203], v[212:215], v[98:113]
	ds_read_b128 v[228:231], v251 offset:40960
	ds_read_b128 v[238:241], v251 offset:45056
	v_mfma_f32_32x32x16_bf16 v[34:49], v[200:203], v[216:219], v[34:49]
	s_cmp_lt_u32 s56, s57
	s_cselect_b32 s60, 0x80, 0
	s_add_u32 s52, s52, s60
	s_addc_u32 s53, s53, 0
	s_add_u32 s54, s54, s60
	s_addc_u32 s55, s55, 0
	s_cmp_eq_u32 s56, s63
	s_cselect_b32 s52, s64, s52
	s_cselect_b32 s53, s65, s53
	s_cselect_b32 s54, s66, s54
	s_cselect_b32 s55, s67, s55
	v_mfma_f32_32x32x16_bf16 v[82:97], v[204:207], v[212:215], v[82:97]
	v_mfma_f32_32x32x16_bf16 v[18:33], v[204:207], v[216:219], v[18:33]
	v_mfma_f32_32x32x16_bf16 v[66:81], v[208:211], v[212:215], v[66:81]
	v_mfma_f32_32x32x16_bf16 v[2:17], v[208:211], v[216:219], v[2:17]
	s_waitcnt lgkmcnt(0)
	v_mfma_f32_32x32x16_bf16 v[114:129], v[220:223], v[242:245], v[114:129]
	v_mfma_f32_32x32x16_bf16 v[50:65], v[220:223], v[246:249], v[50:65]
	v_mfma_f32_32x32x16_bf16 v[98:113], v[224:227], v[242:245], v[98:113]
	v_mfma_f32_32x32x16_bf16 v[34:49], v[224:227], v[246:249], v[34:49]
	v_mfma_f32_32x32x16_bf16 v[82:97], v[228:231], v[242:245], v[82:97]
	v_mfma_f32_32x32x16_bf16 v[18:33], v[228:231], v[246:249], v[18:33]
	v_mfma_f32_32x32x16_bf16 v[66:81], v[238:241], v[242:245], v[66:81]
	v_mfma_f32_32x32x16_bf16 v[2:17], v[238:241], v[246:249], v[2:17]
	s_waitcnt vmcnt(0)
	s_barrier
	ds_read_b128 v[196:199], v194 offset:0
	ds_read_b128 v[212:215], v160 offset:0
	ds_read_b128 v[216:219], v160 offset:4096
	ds_read_b128 v[200:203], v194 offset:4096
	ds_read_b128 v[204:207], v194 offset:8192
	ds_read_b128 v[208:211], v194 offset:12288
	s_cmp_lt_u32 s56, s57
	s_cbranch_scc1 .Lg_inproj_loop
	s_waitcnt lgkmcnt(0)
	s_nop 7
	s_nop 7
	s_branch .LBB0_195

; DI int tid512() { int t = threadIdx.x; asm volatile("" : "+v"(t)); return t; }
; DI unsigned voff256(size_t ld) { const int t = tid512(); return (unsigned)(((size_t)(t >> 3) * ld + (t & 7) * 8) * 2); }
; DI int tile_of(int i, int ntiles) {
;   const int G = gridDim.x, b = blockIdx.x;
;   if (G & 7) { int L = b + i * G; return L < ntiles ? L : -1; }
;   const int q = (ntiles + 7) >> 3, nb = G >> 3, x = b & 7, loc = (b >> 3) + i * nb;
;   if (loc >= q) return -1;
;   const int L = x * q + loc;
;   return L < ntiles ? L : -1;
; }
; DI void gateup256(const Params& p, int layer, char* smem) {
;     ...
;   for (int i = 0;; ++i) {
;     const int L = tile_of(i, 32 * 44);
;     if (L < 0) break;
;     int tm, nb; tile_mn(L, 32, 44, tm, nb);
;     const int t = tid512(), lane = t & 63, w = t >> 6, wm = w >> 2, wn = w & 3, r = lane & 31, h = lane >> 5;
;     const unsigned bvo = (unsigned)(((size_t)((t >> 3) & 31) * DM + (t & 7) * 8) * 2 + ((((t >> 3) >> 5) & 1) ? (O_WU - O_WG) : 0));
;     f32x16 acc[4][2]; zero_acc256(acc);
;     gemm256((const char*)(H + (size_t)(256 + tm * 256) * DM), voff256(DM), (size_t)128 * DM, (const char*)(WG + (size_t)(nb * 128) * DM), bvo, (size_t)64 * DM, DM / 64, smem, acc);
.LBB0_1564:
	s_mul_hi_u32 s4, s6, 0xba2e8ba3
	s_lshr_b32 s4, s4, 7
	s_lshl_b32 s5, s4, 2
	s_sub_i32 s7, 32, s5
	s_min_i32 s7, s7, 4
	s_abs_i32 s9, s7
	v_cvt_f32_u32_e32 v2, s9
	s_sub_i32 s10, 0, s9
	s_mulk_i32 s4, 0xff50
	s_add_i32 s4, s4, s6
	v_rcp_iflag_f32_e32 v2, v2
	s_abs_i32 s8, s4
	s_xor_b32 s6, s4, s7
	s_ashr_i32 s6, s6, 31
	v_mul_f32_e32 v2, 0x4f7ffffe, v2
	v_cvt_u32_f32_e32 v2, v2
	v_mov_b32_e32 v193, v0
	v_mov_b32_e32 v37, v181
	v_readfirstlane_b32 s11, v2
	s_mul_i32 s10, s10, s11
	s_mul_hi_u32 s10, s11, s10
	s_add_i32 s11, s11, s10
	s_mul_hi_u32 s10, s8, s11
	s_mul_i32 s11, s10, s9
	s_sub_i32 s8, s8, s11
	s_add_i32 s11, s10, 1
	s_sub_i32 s15, s8, s9
	s_cmp_ge_u32 s8, s9
	s_cselect_b32 s10, s11, s10
	s_cselect_b32 s8, s15, s8
	s_add_i32 s11, s10, 1
	s_cmp_ge_u32 s8, s9
	s_cselect_b32 s8, s11, s10
	s_xor_b32 s8, s8, s6
	s_sub_i32 s6, s8, s6
	s_mul_i32 s7, s6, s7
	s_sub_i32 s4, s4, s7
	s_add_i32 s4, s4, s5
	s_lshl_b32 s4, s4, 8
	s_addk_i32 s4, 0x100
	v_lshlrev_b32_e32 v2, 9, v193
	v_lshlrev_b32_e32 v3, 4, v193
	v_bfe_i32 v4, v193, 8, 1
	s_ashr_i32 s5, s4, 31
	v_and_b32_e32 v2, 0x1f000, v2
	v_and_b32_e32 v3, 0x70, v3
	v_and_b32_e32 v4, 0x2c00000, v4
	s_lshl_b64 s[8:9], s[4:5], 12
	v_or3_b32 v36, v2, v3, v4
	s_add_u32 s8, s92, s8
	v_mov_b32_e32 v2, v0
	s_addc_u32 s9, s93, s9
	s_lshl_b32 s6, s6, 7
	v_lshlrev_b32_e32 v3, 4, v2
	v_and_b32_e32 v3, 0x70, v3
	v_lshlrev_b32_e32 v2, 9, v2
	s_movk_i32 s5, 0xf000
	s_ashr_i32 s7, s6, 31
	v_and_or_b32 v180, v2, s5, v3
	s_lshl_b64 s[10:11], s[6:7], 12
	s_add_u32 s10, s12, s10
	v_lshl_add_u64 v[162:163], s[8:9], 0, v[180:181]
	s_addc_u32 s11, s13, s11
	v_add_co_u32_e32 v12, vcc, s84, v162
	v_lshl_add_u64 v[164:165], s[10:11], 0, v[36:37]
	s_nop 0
	v_addc_co_u32_e32 v13, vcc, 0, v163, vcc
	v_add_co_u32_e32 v16, vcc, s87, v164
	s_mov_b32 s5, 32
	v_mov_b32_e32 v2, v0
	v_addc_co_u32_e32 v17, vcc, 0, v165, vcc
	v_add_co_u32_e32 v20, vcc, s31, v162
	v_lshlrev_b32_e32 v4, 4, v2
	v_and_b32_e32 v38, 0x70, v4
	v_lshrrev_b32_e32 v132, 6, v0
	s_nop 0
	v_readfirstlane_b32 s61, v132
	v_and_b32_e32 v132, 63, v0
	v_and_b32_e32 v133, 31, v132
	v_lshrrev_b32_e32 v136, 5, v132
	v_bfe_u32 v137, v133, 1, 3
	v_lshlrev_b32_e32 v133, 7, v133
	s_lshr_b32 s60, s61, 2
	s_lshl_b32 s60, s60, 14
	s_add_i32 s60, s60, 16
	s_and_b32 s62, s61, 3
	s_lshl_b32 s62, s62, 13
	s_add_i32 s62, s62, 0x10010
	v_add_u32_e32 v194, 0, v136
	v_xor_b32_e32 v194, v194, v137
	v_lshl_add_u32 v194, v194, 4, v133
	v_add_u32_e32 v160, s62, v194
	v_add_u32_e32 v194, s60, v194
	v_add_u32_e32 v195, 2, v136
	v_xor_b32_e32 v195, v195, v137
	v_lshl_add_u32 v195, v195, 4, v133
	v_add_u32_e32 v161, s62, v195
	v_add_u32_e32 v195, s60, v195
	v_add_u32_e32 v250, 4, v136
	v_xor_b32_e32 v250, v250, v137
	v_lshl_add_u32 v250, v250, 4, v133
	v_add_u32_e32 v162, s62, v250
	v_add_u32_e32 v250, s60, v250
	v_add_u32_e32 v251, 6, v136
	v_xor_b32_e32 v251, v251, v137
	v_lshl_add_u32 v251, v251, 4, v133
	v_add_u32_e32 v163, s62, v251
	v_add_u32_e32 v251, s60, v251
	v_lshrrev_b32_e32 v133, 3, v132
	s_mov_b32 s60, 0x1000
	v_mul_lo_u32 v133, v133, s60
	v_and_b32_e32 v136, 7, v132
	v_lshrrev_b32_e32 v137, 4, v132
	v_xor_b32_e32 v164, v137, v136
	v_lshl_add_u32 v164, v164, 4, v133
	v_add_u32_e32 v165, 4, v137
	v_xor_b32_e32 v165, v165, v136
	v_lshl_add_u32 v165, v165, 4, v133
	v_add_u32_e32 v165, 0x8000, v165
	v_xor_b32_e32 v130, v137, v136
	v_lshl_add_u32 v130, v130, 4, v133
	v_add_u32_e32 v130, 0x10000, v130
	v_add_u32_e32 v131, 4, v137
	v_xor_b32_e32 v131, v131, v136
	v_lshl_add_u32 v131, v131, 4, v133
	v_add_u32_e32 v131, 0x18000, v131
	s_mul_i32 s60, s61, 0x20000
	s_add_u32 s52, s8, s60
	s_addc_u32 s53, s9, 0
	s_lshr_b32 s60, s61, 1
	s_mul_i32 s60, s60, 0x20000
	s_and_b32 s62, s61, 1
	s_mul_i32 s62, s62, 0x2c00000
	s_add_u32 s60, s60, s62
	s_add_u32 s54, s10, s60
	s_addc_u32 s55, s11, 0
	s_lshl_b32 s58, s61, 12
	s_add_i32 s58, s58, 16
	s_add_i32 s59, s58, 0x10000
	s_mov_b32 s56, 0
	s_mov_b32 s57, 31
	s_add_u32 s64, s52, 0x0
	s_addc_u32 s65, s53, 0
	s_add_u32 s66, s54, 0x400000
	s_addc_u32 s67, s55, 0
	s_and_b64 s[62:63], exec, s[40:41]
	s_cselect_b32 s62, 0, 1
	s_add_i32 s60, s14, 1
	s_mul_i32 s60, s60, s88
	s_add_i32 s60, s60, s33
	s_cmp_lt_u32 s60, 176
	s_cselect_b32 s63, s57, -1
	s_cmp_eq_u32 s62, 1
	s_cselect_b32 s63, -1, s63
	s_cbranch_scc1 .Lg_gateup_first
	s_cmp_eq_u32 s14, 0
	s_cbranch_scc1 .Lg_gateup_first
	s_cmp_lt_u32 s56, s57
	s_cselect_b32 s60, 0x80, 0
	s_add_u32 s52, s52, s60
	s_addc_u32 s53, s53, 0
	s_add_u32 s54, s54, s60
	s_addc_u32 s55, s55, 0
	s_cmp_eq_u32 s56, s63
	s_cselect_b32 s52, s64, s52
	s_cselect_b32 s53, s65, s53
	s_cselect_b32 s54, s66, s54
	s_cselect_b32 s55, s67, s55
	v_mov_b64_e32 v[114:115], 0
	v_mov_b64_e32 v[116:117], 0
	v_mov_b64_e32 v[118:119], 0
	v_mov_b64_e32 v[120:121], 0
	v_mov_b64_e32 v[122:123], 0
	v_mov_b64_e32 v[124:125], 0
	v_mov_b64_e32 v[126:127], 0
	v_mov_b64_e32 v[128:129], 0
	v_mov_b64_e32 v[98:99], 0
	v_mov_b64_e32 v[100:101], 0
	v_mov_b64_e32 v[102:103], 0
	v_mov_b64_e32 v[104:105], 0
	v_mov_b64_e32 v[106:107], 0
	v_mov_b64_e32 v[108:109], 0
	v_mov_b64_e32 v[110:111], 0
	v_mov_b64_e32 v[112:113], 0
	v_mov_b64_e32 v[82:83], 0
	v_mov_b64_e32 v[84:85], 0
	v_mov_b64_e32 v[86:87], 0
	v_mov_b64_e32 v[88:89], 0
	v_mov_b64_e32 v[90:91], 0
	v_mov_b64_e32 v[92:93], 0
	v_mov_b64_e32 v[94:95], 0
	v_mov_b64_e32 v[96:97], 0
	v_mov_b64_e32 v[66:67], 0
	v_mov_b64_e32 v[68:69], 0
	v_mov_b64_e32 v[70:71], 0
	v_mov_b64_e32 v[72:73], 0
	v_mov_b64_e32 v[74:75], 0
	v_mov_b64_e32 v[76:77], 0
	v_mov_b64_e32 v[78:79], 0
	v_mov_b64_e32 v[80:81], 0
	v_mov_b64_e32 v[50:51], 0
	v_mov_b64_e32 v[52:53], 0
	v_mov_b64_e32 v[54:55], 0
	v_mov_b64_e32 v[56:57], 0
	v_mov_b64_e32 v[58:59], 0
	v_mov_b64_e32 v[60:61], 0
	v_mov_b64_e32 v[62:63], 0
	v_mov_b64_e32 v[64:65], 0
	v_mov_b64_e32 v[34:35], 0
	v_mov_b64_e32 v[36:37], 0
	v_mov_b64_e32 v[38:39], 0
	v_mov_b64_e32 v[40:41], 0
	v_mov_b64_e32 v[42:43], 0
	v_mov_b64_e32 v[44:45], 0
	v_mov_b64_e32 v[46:47], 0
	v_mov_b64_e32 v[48:49], 0
	v_mov_b64_e32 v[18:19], 0
	v_mov_b64_e32 v[20:21], 0
	v_mov_b64_e32 v[22:23], 0
	v_mov_b64_e32 v[24:25], 0
	v_mov_b64_e32 v[26:27], 0
	v_mov_b64_e32 v[28:29], 0
	v_mov_b64_e32 v[30:31], 0
	v_mov_b64_e32 v[32:33], 0
	v_mov_b64_e32 v[2:3], 0
	v_mov_b64_e32 v[4:5], 0
	v_mov_b64_e32 v[6:7], 0
	v_mov_b64_e32 v[8:9], 0
	v_mov_b64_e32 v[10:11], 0
	v_mov_b64_e32 v[12:13], 0
	v_mov_b64_e32 v[14:15], 0
	v_mov_b64_e32 v[16:17], 0
	s_branch .Lg_gateup_go
; DI int tid512() { int t = threadIdx.x; asm volatile("" : "+v"(t)); return t; }
; DI void gemm256(const char* a_u, unsigned a_voff, size_t astep, const char* b_u, unsigned b_voff, size_t bstep, int nk, char* smem, f32x16 (&acc)[4][2]) {
;   asm volatile("" : "+s"(nk));
;   const int t = tid512(), lane = t & 63, w = t >> 6, wm = w >> 2, wn = w & 3, r = lane & 31, h = lane >> 5;
;   const int soff = (t >> 3) * LROW + (t & 7) * 16;
;   const int aoff = (128 * wm + r) * LROW + h * 16, boff = T2 + (64 * wn + r) * LROW + h * 16;
;   u32x4 ra[4], rb[4];
; #pragma unroll
;   for (int i = 0; i < 4; ++i) { ra[i] = *(const u32x4*)(a_u + i * astep + a_voff); rb[i] = *(const u32x4*)(b_u + i * bstep + b_voff); }
;   __syncthreads();
; #pragma unroll
;   for (int i = 0; i < 4; ++i) { *(u32x4*)(smem + soff + i * 64 * LROW) = ra[i]; *(u32x4*)(smem + T2 + soff + i * 64 * LROW) = rb[i]; }
;   const int last = nk - 1;
;   {
;     const int k1 = last < 1 ? last : 1;
; #pragma unroll
;     for (int i = 0; i < 4; ++i) { ra[i] = *(const u32x4*)(a_u + i * astep + k1 * 128 + a_voff); rb[i] = *(const u32x4*)(b_u + i * bstep + k1 * 128 + b_voff); }
;   }
;   __syncthreads();
.Lg_gateup_first:
	s_barrier
	s_add_u32 m0, s58, 0x0
	s_nop 0
	global_load_lds_dwordx4 v164, s[52:53]
	s_add_u32 m0, s58, 0x400
	s_nop 0
	global_load_lds_dwordx4 v165, s[52:53]
	s_add_u32 m0, s58, 0x800
	s_nop 0
	global_load_lds_dwordx4 v130, s[52:53]
	s_add_u32 m0, s58, 0xc00
	s_nop 0
	global_load_lds_dwordx4 v131, s[52:53]
	s_add_u32 m0, s59, 0x0
	s_nop 0
	global_load_lds_dwordx4 v164, s[54:55]
	s_add_u32 m0, s59, 0x400
	s_nop 0
	global_load_lds_dwordx4 v165, s[54:55]
	s_add_u32 m0, s59, 0x800
	s_nop 0
	global_load_lds_dwordx4 v130, s[54:55]
	s_add_u32 m0, s59, 0xc00
	s_nop 0
	global_load_lds_dwordx4 v131, s[54:55]
	s_cmp_lt_u32 s56, s57
	s_cselect_b32 s60, 0x80, 0
	s_add_u32 s52, s52, s60
	s_addc_u32 s53, s53, 0
	s_add_u32 s54, s54, s60
	s_addc_u32 s55, s55, 0
	s_cmp_eq_u32 s56, s63
	s_cselect_b32 s52, s64, s52
	s_cselect_b32 s53, s65, s53
	s_cselect_b32 s54, s66, s54
	s_cselect_b32 s55, s67, s55
	v_mov_b64_e32 v[114:115], 0
	v_mov_b64_e32 v[116:117], 0
	v_mov_b64_e32 v[118:119], 0
	v_mov_b64_e32 v[120:121], 0
	v_mov_b64_e32 v[122:123], 0
	v_mov_b64_e32 v[124:125], 0
	v_mov_b64_e32 v[126:127], 0
	v_mov_b64_e32 v[128:129], 0
	v_mov_b64_e32 v[98:99], 0
	v_mov_b64_e32 v[100:101], 0
	v_mov_b64_e32 v[102:103], 0
	v_mov_b64_e32 v[104:105], 0
	v_mov_b64_e32 v[106:107], 0
	v_mov_b64_e32 v[108:109], 0
	v_mov_b64_e32 v[110:111], 0
	v_mov_b64_e32 v[112:113], 0
	v_mov_b64_e32 v[82:83], 0
	v_mov_b64_e32 v[84:85], 0
	v_mov_b64_e32 v[86:87], 0
	v_mov_b64_e32 v[88:89], 0
	v_mov_b64_e32 v[90:91], 0
	v_mov_b64_e32 v[92:93], 0
	v_mov_b64_e32 v[94:95], 0
	v_mov_b64_e32 v[96:97], 0
	v_mov_b64_e32 v[66:67], 0
	v_mov_b64_e32 v[68:69], 0
	v_mov_b64_e32 v[70:71], 0
	v_mov_b64_e32 v[72:73], 0
	v_mov_b64_e32 v[74:75], 0
	v_mov_b64_e32 v[76:77], 0
	v_mov_b64_e32 v[78:79], 0
	v_mov_b64_e32 v[80:81], 0
	v_mov_b64_e32 v[50:51], 0
	v_mov_b64_e32 v[52:53], 0
	v_mov_b64_e32 v[54:55], 0
	v_mov_b64_e32 v[56:57], 0
	v_mov_b64_e32 v[58:59], 0
	v_mov_b64_e32 v[60:61], 0
	v_mov_b64_e32 v[62:63], 0
	v_mov_b64_e32 v[64:65], 0
	v_mov_b64_e32 v[34:35], 0
	v_mov_b64_e32 v[36:37], 0
	v_mov_b64_e32 v[38:39], 0
	v_mov_b64_e32 v[40:41], 0
	v_mov_b64_e32 v[42:43], 0
	v_mov_b64_e32 v[44:45], 0
	v_mov_b64_e32 v[46:47], 0
	v_mov_b64_e32 v[48:49], 0
	v_mov_b64_e32 v[18:19], 0
	v_mov_b64_e32 v[20:21], 0
	v_mov_b64_e32 v[22:23], 0
	v_mov_b64_e32 v[24:25], 0
	v_mov_b64_e32 v[26:27], 0
	v_mov_b64_e32 v[28:29], 0
	v_mov_b64_e32 v[30:31], 0
	v_mov_b64_e32 v[32:33], 0
	v_mov_b64_e32 v[2:3], 0
	v_mov_b64_e32 v[4:5], 0
	v_mov_b64_e32 v[6:7], 0
	v_mov_b64_e32 v[8:9], 0
	v_mov_b64_e32 v[10:11], 0
	v_mov_b64_e32 v[12:13], 0
	v_mov_b64_e32 v[14:15], 0
	v_mov_b64_e32 v[16:17], 0
	s_waitcnt vmcnt(0)
	s_barrier

; #define MFMA32(a, b, c) __builtin_amdgcn_mfma_f32_32x32x16_bf16((a), (b), (c), 0, 0, 0)
; DI void gemm256(const char* a_u, unsigned a_voff, size_t astep, const char* b_u, unsigned b_voff, size_t bstep, int nk, char* smem, f32x16 (&acc)[4][2]) {
;     ...
;   for (int kt = 0; kt < nk; ++kt) {
;     const int cur = kt & 1, k2 = (kt + 2 < last) ? kt + 2 : last;
;     const char* S = smem + cur * 2 * T2;
;     char* D = smem + (cur ^ 1) * 2 * T2;
;     const char* an = a_u + (size_t)k2 * 128;
;     const char* bn = b_u + (size_t)k2 * 128;
; #pragma unroll
;     for (int s = 0; s < 4; ++s) {
;       bf16x8 a[4], b[2];
; #pragma unroll
;       for (int mi = 0; mi < 4; ++mi) a[mi] = *(const bf16x8*)(S + aoff + mi * 32 * LROW + s * 32);
; #pragma unroll
;       for (int ni = 0; ni < 2; ++ni) b[ni] = *(const bf16x8*)(S + boff + ni * 32 * LROW + s * 32);
;       *(u32x4*)(D + soff + s * 64 * LROW) = ra[s];
;       *(u32x4*)(D + T2 + soff + s * 64 * LROW) = rb[s];
;       ra[s] = *(const u32x4*)(an + s * astep + a_voff);
;       rb[s] = *(const u32x4*)(bn + s * bstep + b_voff);
; #pragma unroll
;       for (int mi = 0; mi < 4; ++mi)
; #pragma unroll
;         for (int ni = 0; ni < 2; ++ni) acc[mi][ni] = MFMA32(a[mi], b[ni], acc[mi][ni]);
;     }
;     __syncthreads();
;   }
.Lg_gateup_loop:
	s_add_i32 s56, s56, 1
	s_add_u32 m0, s58, 0x8000
	s_nop 0
	global_load_lds_dwordx4 v164, s[52:53]
	s_add_u32 m0, s58, 0x8400
	s_nop 0
	global_load_lds_dwordx4 v165, s[52:53]
	s_add_u32 m0, s58, 0x8800
	s_nop 0
	global_load_lds_dwordx4 v130, s[52:53]
	s_add_u32 m0, s58, 0x8c00
	s_nop 0
	global_load_lds_dwordx4 v131, s[52:53]
	s_add_u32 m0, s59, 0x8000
	s_nop 0
	global_load_lds_dwordx4 v164, s[54:55]
	s_add_u32 m0, s59, 0x8400
	s_nop 0
	global_load_lds_dwordx4 v165, s[54:55]
	s_add_u32 m0, s59, 0x8800
	s_nop 0
	global_load_lds_dwordx4 v130, s[54:55]
	s_add_u32 m0, s59, 0x8c00
	s_nop 0
	global_load_lds_dwordx4 v131, s[54:55]
	s_waitcnt lgkmcnt(0)
	v_mfma_f32_32x32x16_bf16 v[114:129], v[196:199], v[212:215], v[114:129]
	ds_read_b128 v[220:223], v195 offset:0
	ds_read_b128 v[242:245], v161 offset:0
	v_mfma_f32_32x32x16_bf16 v[98:113], v[196:199], v[216:219], v[98:113]
	ds_read_b128 v[246:249], v161 offset:4096
	ds_read_b128 v[224:227], v195 offset:4096
	v_mfma_f32_32x32x16_bf16 v[82:97], v[200:203], v[212:215], v[82:97]
	ds_read_b128 v[228:231], v195 offset:8192
	ds_read_b128 v[238:241], v195 offset:12288
	v_mfma_f32_32x32x16_bf16 v[66:81], v[200:203], v[216:219], v[66:81]
	v_mfma_f32_32x32x16_bf16 v[50:65], v[204:207], v[212:215], v[50:65]
	v_mfma_f32_32x32x16_bf16 v[34:49], v[204:207], v[216:219], v[34:49]
	v_mfma_f32_32x32x16_bf16 v[18:33], v[208:211], v[212:215], v[18:33]
	v_mfma_f32_32x32x16_bf16 v[2:17], v[208:211], v[216:219], v[2:17]
	s_waitcnt lgkmcnt(0)
	v_mfma_f32_32x32x16_bf16 v[114:129], v[220:223], v[242:245], v[114:129]
	ds_read_b128 v[196:199], v250 offset:0
	ds_read_b128 v[212:215], v162 offset:0
	v_mfma_f32_32x32x16_bf16 v[98:113], v[220:223], v[246:249], v[98:113]
	ds_read_b128 v[216:219], v162 offset:4096
	ds_read_b128 v[200:203], v250 offset:4096
	v_mfma_f32_32x32x16_bf16 v[82:97], v[224:227], v[242:245], v[82:97]
	ds_read_b128 v[204:207], v250 offset:8192
	ds_read_b128 v[208:211], v250 offset:12288
	v_mfma_f32_32x32x16_bf16 v[66:81], v[224:227], v[246:249], v[66:81]
	v_mfma_f32_32x32x16_bf16 v[50:65], v[228:231], v[242:245], v[50:65]
	v_mfma_f32_32x32x16_bf16 v[34:49], v[228:231], v[246:249], v[34:49]
	v_mfma_f32_32x32x16_bf16 v[18:33], v[238:241], v[242:245], v[18:33]
	v_mfma_f32_32x32x16_bf16 v[2:17], v[238:241], v[246:249], v[2:17]
	s_waitcnt lgkmcnt(0)
	v_mfma_f32_32x32x16_bf16 v[114:129], v[196:199], v[212:215], v[114:129]
	ds_read_b128 v[220:223], v251 offset:0
	ds_read_b128 v[242:245], v163 offset:0
	v_mfma_f32_32x32x16_bf16 v[98:113], v[196:199], v[216:219], v[98:113]
	ds_read_b128 v[246:249], v163 offset:4096
	ds_read_b128 v[224:227], v251 offset:4096
	v_mfma_f32_32x32x16_bf16 v[82:97], v[200:203], v[212:215], v[82:97]
	ds_read_b128 v[228:231], v251 offset:8192
	ds_read_b128 v[238:241], v251 offset:12288
	v_mfma_f32_32x32x16_bf16 v[66:81], v[200:203], v[216:219], v[66:81]
	s_cmp_lt_u32 s56, s57
	s_cselect_b32 s60, 0x80, 0
	s_add_u32 s52, s52, s60
	s_addc_u32 s53, s53, 0
	s_add_u32 s54, s54, s60
	s_addc_u32 s55, s55, 0
	s_cmp_eq_u32 s56, s63
	s_cselect_b32 s52, s64, s52
	s_cselect_b32 s53, s65, s53
	s_cselect_b32 s54, s66, s54
	s_cselect_b32 s55, s67, s55
	v_mfma_f32_32x32x16_bf16 v[50:65], v[204:207], v[212:215], v[50:65]
	v_mfma_f32_32x32x16_bf16 v[34:49], v[204:207], v[216:219], v[34:49]
	v_mfma_f32_32x32x16_bf16 v[18:33], v[208:211], v[212:215], v[18:33]
	v_mfma_f32_32x32x16_bf16 v[2:17], v[208:211], v[216:219], v[2:17]
	s_waitcnt lgkmcnt(0)
	v_mfma_f32_32x32x16_bf16 v[114:129], v[220:223], v[242:245], v[114:129]
	v_mfma_f32_32x32x16_bf16 v[98:113], v[220:223], v[246:249], v[98:113]
	v_mfma_f32_32x32x16_bf16 v[82:97], v[224:227], v[242:245], v[82:97]
	v_mfma_f32_32x32x16_bf16 v[66:81], v[224:227], v[246:249], v[66:81]
	v_mfma_f32_32x32x16_bf16 v[50:65], v[228:231], v[242:245], v[50:65]
	v_mfma_f32_32x32x16_bf16 v[34:49], v[228:231], v[246:249], v[34:49]
	v_mfma_f32_32x32x16_bf16 v[18:33], v[238:241], v[242:245], v[18:33]
	v_mfma_f32_32x32x16_bf16 v[2:17], v[238:241], v[246:249], v[2:17]
	s_waitcnt vmcnt(0)
	s_barrier
; #define MFMA32(a, b, c) __builtin_amdgcn_mfma_f32_32x32x16_bf16((a), (b), (c), 0, 0, 0)
; DI void gemm256(const char* a_u, unsigned a_voff, size_t astep, const char* b_u, unsigned b_voff, size_t bstep, int nk, char* smem, f32x16 (&acc)[4][2]) {
;     ...
;   for (int kt = 0; kt < nk; ++kt) {
;     const int cur = kt & 1, k2 = (kt + 2 < last) ? kt + 2 : last;
;     const char* S = smem + cur * 2 * T2;
;     char* D = smem + (cur ^ 1) * 2 * T2;
;     const char* an = a_u + (size_t)k2 * 128;
;     const char* bn = b_u + (size_t)k2 * 128;
; #pragma unroll
;     for (int s = 0; s < 4; ++s) {
;       bf16x8 a[4], b[2];
; #pragma unroll
;       for (int mi = 0; mi < 4; ++mi) a[mi] = *(const bf16x8*)(S + aoff + mi * 32 * LROW + s * 32);
; #pragma unroll
;       for (int ni = 0; ni < 2; ++ni) b[ni] = *(const bf16x8*)(S + boff + ni * 32 * LROW + s * 32);
;       *(u32x4*)(D + soff + s * 64 * LROW) = ra[s];
;       *(u32x4*)(D + T2 + soff + s * 64 * LROW) = rb[s];
;       ra[s] = *(const u32x4*)(an + s * astep + a_voff);
;       rb[s] = *(const u32x4*)(bn + s * bstep + b_voff);
; #pragma unroll
;       for (int mi = 0; mi < 4; ++mi)
; #pragma unroll
;         for (int ni = 0; ni < 2; ++ni) acc[mi][ni] = MFMA32(a[mi], b[ni], acc[mi][ni]);
;     }
;     __syncthreads();
;   }
	ds_read_b128 v[196:199], v194 offset:32768
	ds_read_b128 v[212:215], v160 offset:32768
	ds_read_b128 v[216:219], v160 offset:36864
	ds_read_b128 v[200:203], v194 offset:36864
	ds_read_b128 v[204:207], v194 offset:40960
	ds_read_b128 v[208:211], v194 offset:45056
	s_add_i32 s56, s56, 1
	s_add_u32 m0, s58, 0x0
	s_nop 0
	global_load_lds_dwordx4 v164, s[52:53]
	s_add_u32 m0, s58, 0x400
	s_nop 0
	global_load_lds_dwordx4 v165, s[52:53]
	s_add_u32 m0, s58, 0x800
	s_nop 0
	global_load_lds_dwordx4 v130, s[52:53]
	s_add_u32 m0, s58, 0xc00
	s_nop 0
	global_load_lds_dwordx4 v131, s[52:53]
	s_add_u32 m0, s59, 0x0
	s_nop 0
	global_load_lds_dwordx4 v164, s[54:55]
	s_add_u32 m0, s59, 0x400
	s_nop 0
	global_load_lds_dwordx4 v165, s[54:55]
	s_add_u32 m0, s59, 0x800
	s_nop 0
	global_load_lds_dwordx4 v130, s[54:55]
	s_add_u32 m0, s59, 0xc00
	s_nop 0
	global_load_lds_dwordx4 v131, s[54:55]
	s_waitcnt lgkmcnt(0)
	v_mfma_f32_32x32x16_bf16 v[114:129], v[196:199], v[212:215], v[114:129]
	ds_read_b128 v[220:223], v195 offset:32768
	ds_read_b128 v[242:245], v161 offset:32768
	v_mfma_f32_32x32x16_bf16 v[98:113], v[196:199], v[216:219], v[98:113]
	ds_read_b128 v[246:249], v161 offset:36864
	ds_read_b128 v[224:227], v195 offset:36864
	v_mfma_f32_32x32x16_bf16 v[82:97], v[200:203], v[212:215], v[82:97]
	ds_read_b128 v[228:231], v195 offset:40960
	ds_read_b128 v[238:241], v195 offset:45056
	v_mfma_f32_32x32x16_bf16 v[66:81], v[200:203], v[216:219], v[66:81]
	v_mfma_f32_32x32x16_bf16 v[50:65], v[204:207], v[212:215], v[50:65]
	v_mfma_f32_32x32x16_bf16 v[34:49], v[204:207], v[216:219], v[34:49]
	v_mfma_f32_32x32x16_bf16 v[18:33], v[208:211], v[212:215], v[18:33]
	v_mfma_f32_32x32x16_bf16 v[2:17], v[208:211], v[216:219], v[2:17]
	s_waitcnt lgkmcnt(0)
	v_mfma_f32_32x32x16_bf16 v[114:129], v[220:223], v[242:245], v[114:129]
	ds_read_b128 v[196:199], v250 offset:32768
	ds_read_b128 v[212:215], v162 offset:32768
	v_mfma_f32_32x32x16_bf16 v[98:113], v[220:223], v[246:249], v[98:113]
	ds_read_b128 v[216:219], v162 offset:36864
	ds_read_b128 v[200:203], v250 offset:36864
	v_mfma_f32_32x32x16_bf16 v[82:97], v[224:227], v[242:245], v[82:97]
	ds_read_b128 v[204:207], v250 offset:40960
	ds_read_b128 v[208:211], v250 offset:45056
	v_mfma_f32_32x32x16_bf16 v[66:81], v[224:227], v[246:249], v[66:81]
	v_mfma_f32_32x32x16_bf16 v[50:65], v[228:231], v[242:245], v[50:65]
	v_mfma_f32_32x32x16_bf16 v[34:49], v[228:231], v[246:249], v[34:49]
	v_mfma_f32_32x32x16_bf16 v[18:33], v[238:241], v[242:245], v[18:33]
	v_mfma_f32_32x32x16_bf16 v[2:17], v[238:241], v[246:249], v[2:17]
	s_waitcnt lgkmcnt(0)
	v_mfma_f32_32x32x16_bf16 v[114:129], v[196:199], v[212:215], v[114:129]
	ds_read_b128 v[220:223], v251 offset:32768
	ds_read_b128 v[242:245], v163 offset:32768
	v_mfma_f32_32x32x16_bf16 v[98:113], v[196:199], v[216:219], v[98:113]
	ds_read_b128 v[246:249], v163 offset:36864
	ds_read_b128 v[224:227], v251 offset:36864
	v_mfma_f32_32x32x16_bf16 v[82:97], v[200:203], v[212:215], v[82:97]
	ds_read_b128 v[228:231], v251 offset:40960
	ds_read_b128 v[238:241], v251 offset:45056
	v_mfma_f32_32x32x16_bf16 v[66:81], v[200:203], v[216:219], v[66:81]
	s_cmp_lt_u32 s56, s57
	s_cselect_b32 s60, 0x80, 0
	s_add_u32 s52, s52, s60
	s_addc_u32 s53, s53, 0
	s_add_u32 s54, s54, s60
	s_addc_u32 s55, s55, 0
	s_cmp_eq_u32 s56, s63
	s_cselect_b32 s52, s64, s52
	s_cselect_b32 s53, s65, s53
	s_cselect_b32 s54, s66, s54
	s_cselect_b32 s55, s67, s55
	v_mfma_f32_32x32x16_bf16 v[50:65], v[204:207], v[212:215], v[50:65]
	v_mfma_f32_32x32x16_bf16 v[34:49], v[204:207], v[216:219], v[34:49]
	v_mfma_f32_32x32x16_bf16 v[18:33], v[208:211], v[212:215], v[18:33]
	v_mfma_f32_32x32x16_bf16 v[2:17], v[208:211], v[216:219], v[2:17]
	s_waitcnt lgkmcnt(0)
	v_mfma_f32_32x32x16_bf16 v[114:129], v[220:223], v[242:245], v[114:129]
	v_mfma_f32_32x32x16_bf16 v[98:113], v[220:223], v[246:249], v[98:113]
	v_mfma_f32_32x32x16_bf16 v[82:97], v[224:227], v[242:245], v[82:97]
	v_mfma_f32_32x32x16_bf16 v[66:81], v[224:227], v[246:249], v[66:81]
	v_mfma_f32_32x32x16_bf16 v[50:65], v[228:231], v[242:245], v[50:65]
	v_mfma_f32_32x32x16_bf16 v[34:49], v[228:231], v[246:249], v[34:49]
	v_mfma_f32_32x32x16_bf16 v[18:33], v[238:241], v[242:245], v[18:33]
	v_mfma_f32_32x32x16_bf16 v[2:17], v[238:241], v[246:249], v[2:17]
	s_waitcnt vmcnt(0)
	s_barrier
	ds_read_b128 v[196:199], v194 offset:0
	ds_read_b128 v[212:215], v160 offset:0
	ds_read_b128 v[216:219], v160 offset:4096
	ds_read_b128 v[200:203], v194 offset:4096
	ds_read_b128 v[204:207], v194 offset:8192
	ds_read_b128 v[208:211], v194 offset:12288
	s_cmp_lt_u32 s56, s57
	s_cbranch_scc1 .Lg_gateup_loop
	s_waitcnt lgkmcnt(0)
	s_nop 7
	s_nop 7
	s_branch .LBB0_1568
